# attention loops restructured (pipelined LDS reads, DMA issue inside PV, branch-free bias) + SwiGLU ssq loads hoisted + SGU gated epilogue loads batched + closing-norm loop software-pipelined
# speedup vs baseline: 1.0099x; 1.0099x over previous
; __device__ __forceinline__ unsigned pk2(float lo, float hi) { unsigned r; asm volatile("v_cvt_pk_bf16_f32 %0, %1, %2" : "=v"(r) : "v"(lo), "v"(hi)); return r; }
; __device__ __forceinline__ float bf_lo(unsigned w) { return __uint_as_float(w << 16); }
; __device__ __forceinline__ float bf_hi(unsigned w) { return __uint_as_float(w & 0xffff0000u); }
; __device__ __forceinline__ void sgu_phase(const PL& P, LAS unsigned char* lds, int vcu, int G, int tid, int wave, int lane) {
;     ...
;             const int t = 16 * wave + fr; const float bias = bs[g * 128 + t]; const size_t row = r0 + t;
; #pragma unroll
;             for (int n = 0; n < 8; ++n) { const int col = g * 128 + 16 * n + 4 * fq; const v2u uu = *(const v2u*)(Z + row * 2048 + col);
;                 v2u w; w.x = pk2(bf_lo(uu.x) * (acc[n][0] + bias), bf_hi(uu.x) * (acc[n][1] + bias)); w.y = pk2(bf_lo(uu.y) * (acc[n][2] + bias), bf_hi(uu.y) * (acc[n][3] + bias));
;                 *(v2u*)(Gt + row * 1024 + col) = w; }
;             __syncthreads();
.LBB0_270:
	v_add_u32_e32 v70, s88, v38
	v_ashrrev_i32_e32 v71, 31, v70
	v_lshl_add_u64 v[70:71], v[70:71], 2, s[92:93]
	global_load_dword v89, v[70:71], off
	v_or_b32_e32 v70, s88, v37
	v_lshlrev_b32_e32 v176, 1, v70
	v_lshl_add_u64 v[70:71], v[66:67], 0, v[176:177]
	global_load_dwordx2 v[100:101], v[70:71], off
	global_load_dwordx2 v[102:103], v[70:71], off offset:32
	global_load_dwordx2 v[104:105], v[70:71], off offset:64
	global_load_dwordx2 v[106:107], v[70:71], off offset:96
	global_load_dwordx2 v[108:109], v[70:71], off offset:128
	global_load_dwordx2 v[110:111], v[70:71], off offset:160
	global_load_dwordx2 v[112:113], v[70:71], off offset:192
	global_load_dwordx2 v[114:115], v[70:71], off offset:224
	v_lshl_add_u64 v[116:117], v[68:69], 0, v[176:177]
	s_add_i32 s76, s76, 1
	s_cmp_eq_u32 s76, 8
	s_waitcnt vmcnt(8)
	v_add_f32_e32 v28, v89, v28
	v_add_f32_e32 v29, v89, v29
	v_add_f32_e32 v30, v89, v30
	v_add_f32_e32 v31, v89, v31
	v_add_f32_e32 v24, v89, v24
	v_add_f32_e32 v25, v89, v25
	v_add_f32_e32 v26, v89, v26
	v_add_f32_e32 v27, v89, v27
	v_add_f32_e32 v20, v89, v20
	v_add_f32_e32 v21, v89, v21
	v_add_f32_e32 v22, v89, v22
	v_add_f32_e32 v23, v89, v23
	v_add_f32_e32 v16, v89, v16
	v_add_f32_e32 v17, v89, v17
	v_add_f32_e32 v18, v89, v18
	v_add_f32_e32 v19, v89, v19
	v_add_f32_e32 v12, v89, v12
	v_add_f32_e32 v13, v89, v13
	v_add_f32_e32 v14, v89, v14
	v_add_f32_e32 v15, v89, v15
	v_add_f32_e32 v8, v89, v8
	v_add_f32_e32 v9, v89, v9
	v_add_f32_e32 v10, v89, v10
	v_add_f32_e32 v11, v89, v11
	v_add_f32_e32 v4, v89, v4
	v_add_f32_e32 v5, v89, v5
	v_add_f32_e32 v6, v89, v6
	v_add_f32_e32 v7, v89, v7
	v_add_f32_e32 v0, v89, v0
	v_add_f32_e32 v1, v89, v1
	v_add_f32_e32 v2, v89, v2
	v_add_f32_e32 v3, v89, v3
	s_waitcnt vmcnt(7)
	v_lshlrev_b32_e32 v118, 16, v100
	v_and_b32_e32 v119, 0xffff0000, v100
	v_mul_f32_e32 v28, v28, v118
	v_mul_f32_e32 v29, v29, v119
	v_cvt_pk_bf16_f32 v28, v28, v29
	v_lshlrev_b32_e32 v118, 16, v101
	v_and_b32_e32 v119, 0xffff0000, v101
	v_mul_f32_e32 v30, v30, v118
	v_mul_f32_e32 v31, v31, v119
	v_cvt_pk_bf16_f32 v29, v30, v31
	global_store_dwordx2 v[116:117], v[28:29], off
	s_waitcnt vmcnt(7)
	v_lshlrev_b32_e32 v118, 16, v102
	v_and_b32_e32 v119, 0xffff0000, v102
	v_mul_f32_e32 v24, v24, v118
	v_mul_f32_e32 v25, v25, v119
	v_cvt_pk_bf16_f32 v24, v24, v25
	v_lshlrev_b32_e32 v118, 16, v103
	v_and_b32_e32 v119, 0xffff0000, v103
	v_mul_f32_e32 v26, v26, v118
	v_mul_f32_e32 v27, v27, v119
	v_cvt_pk_bf16_f32 v25, v26, v27
	global_store_dwordx2 v[116:117], v[24:25], off offset:32
	s_waitcnt vmcnt(7)
	v_lshlrev_b32_e32 v118, 16, v104
	v_and_b32_e32 v119, 0xffff0000, v104
	v_mul_f32_e32 v20, v20, v118
	v_mul_f32_e32 v21, v21, v119
	v_cvt_pk_bf16_f32 v20, v20, v21
	v_lshlrev_b32_e32 v118, 16, v105
	v_and_b32_e32 v119, 0xffff0000, v105
	v_mul_f32_e32 v22, v22, v118
	v_mul_f32_e32 v23, v23, v119
	v_cvt_pk_bf16_f32 v21, v22, v23
	global_store_dwordx2 v[116:117], v[20:21], off offset:64
	s_waitcnt vmcnt(7)
	v_lshlrev_b32_e32 v118, 16, v106
	v_and_b32_e32 v119, 0xffff0000, v106
	v_mul_f32_e32 v16, v16, v118
	v_mul_f32_e32 v17, v17, v119
	v_cvt_pk_bf16_f32 v16, v16, v17
	v_lshlrev_b32_e32 v118, 16, v107
	v_and_b32_e32 v119, 0xffff0000, v107
	v_mul_f32_e32 v18, v18, v118
	v_mul_f32_e32 v19, v19, v119
	v_cvt_pk_bf16_f32 v17, v18, v19
	global_store_dwordx2 v[116:117], v[16:17], off offset:96
	s_waitcnt vmcnt(7)
	v_lshlrev_b32_e32 v118, 16, v108
	v_and_b32_e32 v119, 0xffff0000, v108
	v_mul_f32_e32 v12, v12, v118
	v_mul_f32_e32 v13, v13, v119
	v_cvt_pk_bf16_f32 v12, v12, v13
	v_lshlrev_b32_e32 v118, 16, v109
	v_and_b32_e32 v119, 0xffff0000, v109
	v_mul_f32_e32 v14, v14, v118
	v_mul_f32_e32 v15, v15, v119
	v_cvt_pk_bf16_f32 v13, v14, v15
	global_store_dwordx2 v[116:117], v[12:13], off offset:128
	s_waitcnt vmcnt(7)
	v_lshlrev_b32_e32 v118, 16, v110
	v_and_b32_e32 v119, 0xffff0000, v110
	v_mul_f32_e32 v8, v8, v118
	v_mul_f32_e32 v9, v9, v119
	v_cvt_pk_bf16_f32 v8, v8, v9
	v_lshlrev_b32_e32 v118, 16, v111
	v_and_b32_e32 v119, 0xffff0000, v111
	v_mul_f32_e32 v10, v10, v118
	v_mul_f32_e32 v11, v11, v119
	v_cvt_pk_bf16_f32 v9, v10, v11
	global_store_dwordx2 v[116:117], v[8:9], off offset:160
	s_waitcnt vmcnt(7)
	v_lshlrev_b32_e32 v118, 16, v112
	v_and_b32_e32 v119, 0xffff0000, v112
	v_mul_f32_e32 v4, v4, v118
	v_mul_f32_e32 v5, v5, v119
	v_cvt_pk_bf16_f32 v4, v4, v5
	v_lshlrev_b32_e32 v118, 16, v113
	v_and_b32_e32 v119, 0xffff0000, v113
	v_mul_f32_e32 v6, v6, v118
	v_mul_f32_e32 v7, v7, v119
	v_cvt_pk_bf16_f32 v5, v6, v7
	global_store_dwordx2 v[116:117], v[4:5], off offset:192
	s_waitcnt vmcnt(7)
	v_lshlrev_b32_e32 v118, 16, v114
	v_and_b32_e32 v119, 0xffff0000, v114
	v_mul_f32_e32 v0, v0, v118
	v_mul_f32_e32 v1, v1, v119
	v_cvt_pk_bf16_f32 v0, v0, v1
	v_lshlrev_b32_e32 v118, 16, v115
	v_and_b32_e32 v119, 0xffff0000, v115
	v_mul_f32_e32 v2, v2, v118
	v_mul_f32_e32 v3, v3, v119
	v_cvt_pk_bf16_f32 v1, v2, v3
	global_store_dwordx2 v[116:117], v[0:1], off offset:224
	s_barrier
	s_cbranch_scc1 .LBB0_260

; __device__ __forceinline__ unsigned cvt_pk_bf16(float lo, float hi) { unsigned r; asm volatile("v_cvt_pk_bf16_f32 %0, %1, %2" : "=v"(r) : "v"(lo), "v"(hi)); return r; }
; #define SWG_(gv, uv) ((gv) * (uv) * __builtin_amdgcn_rcpf(1.0f + __builtin_amdgcn_exp2f(-(gv))))
;     __device__ __forceinline__ unsigned u(int i) const { return (unsigned)__builtin_amdgcn_readfirstlane((int)d[i]); }
; __device__ __forceinline__ float row_scale(const float* ssqA, const float* ssqB, int row) {
;     float r = __builtin_amdgcn_rsqf(ssqA[row] * (1.0f / 1024.0f) + 1e-6f);
;     if (ssqB) r *= __builtin_amdgcn_rsqf(r * r * ssqB[row] * (1.0f / 1024.0f) + 1e-6f);
;     return r;
; }
;     static __device__ __forceinline__ void run(const f32x4 (&acc)[2][2][4][2], const Unit& u, int wr, int wc, int fr, int fq, bf16_t* H, int ldh, const float* ssqA, const float* ssqB, const float* bvec) {
;         const int b = (u.pm * BM) >> 13; const int row0 = u.pm * BM + wr * 64 + fr; const int col0 = u.pn * 128 + wc * 32 + 8 * fq;
;         const float* bp = bvec + ((unsigned)b * (unsigned)(2 * ldh) + (unsigned)(u.pn * BM + wc * 32 + 8 * fq));
;         const f32x4 bg0 = *(const f32x4*)bp * 1.4426950408889634f, bg1 = *(const f32x4*)(bp + 4) * 1.4426950408889634f, bu0 = *(const f32x4*)(bp + HALF) * 0.6931471805599453f, bu1 = *(const f32x4*)(bp + HALF + 4) * 0.6931471805599453f;
;     ...
; #pragma unroll
;         for (int ai = 0; ai < 2; ++ai)
; #pragma unroll
;             for (int m = 0; m < 4; ++m) {
;                 const int row = row0 + ai * HALF + m * 16; const float r = row_scale(ssqA, ssqB, row); const float rg = r * 1.4426950408889634f, ru = r * 0.6931471805599453f;
;                 bf16_t* p = H + ((unsigned)row * (unsigned)ldh + (unsigned)col0);
;                 const f32x4 g0 = acc[ai][0][m][0] * rg + bg0, g1 = acc[ai][0][m][1] * rg + bg1, u0 = acc[ai][1][m][0] * ru + bu0, u1 = acc[ai][1][m][1] * ru + bu1;
;                 u32x4 w;
;                 w.x = cvt_pk_bf16(SWG_(g0[0], u0[0]), SWG_(g0[1], u0[1]));
;                 w.y = cvt_pk_bf16(SWG_(g0[2], u0[2]), SWG_(g0[3], u0[3]));
;                 w.z = cvt_pk_bf16(SWG_(g1[0], u1[0]), SWG_(g1[1], u1[1]));
;                 w.w = cvt_pk_bf16(SWG_(g1[2], u1[2]), SWG_(g1[3], u1[3]));
;                 __builtin_nontemporal_store(w, (u32x4*)p);
;                 asm volatile("" ::: "memory");
;             }
.LBB0_546:
	s_andn2_b64 vcc, exec, s[26:27]
	s_cbranch_vccnz .LBB0_564
	v_readlane_b32 s2, v251, 34
	v_lshlrev_b32_e32 v150, 3, v229
	s_lshl_b32 s8, s64, 5
	v_mov_b32_e32 v128, s2
	v_readlane_b32 s2, v251, 35
	ds_read_b32 v130, v128
	v_lshl_or_b32 v132, s62, 8, v150
	v_mov_b32_e32 v128, s2
	v_readlane_b32 s2, v251, 33
	ds_read2_b64 v[144:147], v128 offset1:1
	s_waitcnt lgkmcnt(0)
	v_readfirstlane_b32 s26, v130
	v_mov_b32_e32 v128, s2
	ds_read_b64 v[128:129], v128
	v_or_b32_e32 v132, s8, v132
	v_readfirstlane_b32 s2, v144
	v_readfirstlane_b32 s3, v145
	v_mov_b32_e32 v152, s86
	v_mov_b32_e32 v130, s2
	v_mov_b32_e32 v131, s3
	s_waitcnt lgkmcnt(0)
	v_readfirstlane_b32 s2, v128
	v_readfirstlane_b32 s3, v129
	v_readfirstlane_b32 s28, v146
	v_mov_b32_e32 v128, s2
	v_mov_b32_e32 v129, s3
	s_lshl_b32 s2, s63, 8
	s_lshl_b32 s3, s65, 6
	s_add_i32 s3, s3, s2
	v_or_b32_e32 v148, s3, v230
	s_ashr_i32 s2, s63, 4
	v_ashrrev_i32_e32 v149, 31, v148
	s_and_b32 s2, s2, -2
	v_lshl_add_u64 v[144:145], v[148:149], 2, v[130:131]
	s_mul_i32 s2, s26, s2
	global_load_dword v151, v[144:145], off
	v_add_u32_e32 v176, s2, v132
	v_lshl_add_u64 v[132:133], v[176:177], 2, v[128:129]
	global_load_dwordx4 v[136:139], v[132:133], off offset:16
	global_load_dwordx4 v[140:143], v[132:133], off
	global_load_dwordx4 v[128:131], v[132:133], off offset:528
	s_nop 0
	global_load_dwordx4 v[132:135], v[132:133], off offset:512
	global_load_dword v180, v[144:145], off offset:64
	global_load_dword v181, v[144:145], off offset:128
	global_load_dword v182, v[144:145], off offset:192
	global_load_dword v183, v[144:145], off offset:512
	global_load_dword v184, v[144:145], off offset:576
	global_load_dword v185, v[144:145], off offset:640
	global_load_dword v186, v[144:145], off offset:704
	ds_read_b64 v[152:153], v152
	v_readfirstlane_b32 s29, v147
	s_cmp_lg_u64 s[28:29], 0
	s_cselect_b64 s[10:11], -1, 0
	s_cmp_eq_u64 s[28:29], 0
	s_waitcnt lgkmcnt(0)
	v_readfirstlane_b32 s2, v152
	v_readfirstlane_b32 s3, v153
	s_waitcnt vmcnt(7)
	v_fmamk_f32 v146, v151, 0x3a800000, v222
	v_rsq_f32_e32 v151, v146
	v_lshl_add_u64 v[146:147], v[148:149], 2, s[28:29]
	s_cbranch_scc1 .LBB0_549
	global_load_dword v149, v[146:147], off
	v_mul_f32_e32 v152, v151, v151
	s_waitcnt vmcnt(0)
	v_mul_f32_e32 v149, v152, v149
	v_fmamk_f32 v149, v149, 0x3a800000, v222
	v_rsq_f32_e32 v149, v149
	s_nop 0
	v_mul_f32_e32 v151, v151, v149
.LBB0_549:
	s_lshl_b32 s9, s62, 7
	s_or_b32 s8, s8, s9
	v_or_b32_e32 v149, s8, v150
	s_mov_b32 s8, 0x3fb8aa3b
	v_pk_mul_f32 v[142:143], v[142:143], s[8:9] op_sel_hi:[1,0]
	v_pk_mul_f32 v[140:141], v[140:141], s[8:9] op_sel_hi:[1,0]
	v_pk_mul_f32 v[138:139], v[138:139], s[8:9] op_sel_hi:[1,0]
	v_pk_mul_f32 v[136:137], v[136:137], s[8:9] op_sel_hi:[1,0]
	s_mov_b32 s8, 0x3f317218
	v_mul_f32_e32 v150, 0x3fb8aa3b, v151
	v_pk_mul_f32 v[134:135], v[134:135], s[8:9] op_sel_hi:[1,0]
	v_pk_mul_f32 v[132:133], v[132:133], s[8:9] op_sel_hi:[1,0]
	v_mul_f32_e32 v152, 0x3f317218, v151
	v_pk_fma_f32 v[124:125], v[124:125], v[150:151], v[140:141] op_sel_hi:[1,0,1]
	v_pk_fma_f32 v[118:119], v[118:119], v[152:153], v[134:135] op_sel_hi:[1,0,1]
	v_pk_fma_f32 v[116:117], v[116:117], v[152:153], v[132:133] op_sel_hi:[1,0,1]
	v_exp_f32_e64 v153, -v124
	v_pk_mul_f32 v[130:131], v[130:131], s[8:9] op_sel_hi:[1,0]
	v_pk_mul_f32 v[128:129], v[128:129], s[8:9] op_sel_hi:[1,0]
	v_pk_fma_f32 v[126:127], v[126:127], v[150:151], v[142:143] op_sel_hi:[1,0,1]
	v_pk_fma_f32 v[122:123], v[122:123], v[150:151], v[138:139] op_sel_hi:[1,0,1]
	v_pk_fma_f32 v[120:121], v[120:121], v[150:151], v[136:137] op_sel_hi:[1,0,1]
	v_pk_fma_f32 v[150:151], v[114:115], v[152:153], v[130:131] op_sel_hi:[1,0,1]
	v_pk_fma_f32 v[114:115], v[112:113], v[152:153], v[128:129] op_sel_hi:[1,0,1]
	v_exp_f32_e64 v112, -v125
	v_add_f32_e32 v113, 1.0, v153
	v_rcp_f32_e32 v113, v113
	v_mul_f32_e32 v116, v124, v116
	v_add_f32_e32 v112, 1.0, v112
	v_rcp_f32_e32 v112, v112
	v_mul_f32_e32 v113, v116, v113
	v_mul_f32_e32 v116, v125, v117
	v_exp_f32_e64 v117, -v126
	v_mul_f32_e32 v112, v116, v112
	v_cvt_pk_bf16_f32 v112, v113, v112
	v_exp_f32_e64 v113, -v127
	v_add_f32_e32 v116, 1.0, v117
	v_rcp_f32_e32 v116, v116
	v_mul_f32_e32 v117, v126, v118
	v_add_f32_e32 v113, 1.0, v113
	v_rcp_f32_e32 v113, v113
	v_mul_f32_e32 v116, v117, v116
	v_mul_f32_e32 v117, v127, v119
	v_exp_f32_e64 v118, -v120
	v_mul_f32_e32 v113, v117, v113
	v_cvt_pk_bf16_f32 v113, v116, v113
	v_exp_f32_e64 v116, -v121
	v_add_f32_e32 v117, 1.0, v118
	v_rcp_f32_e32 v117, v117
	v_mul_f32_e32 v114, v120, v114
	v_add_f32_e32 v116, 1.0, v116
	v_rcp_f32_e32 v116, v116
	v_mul_f32_e32 v114, v114, v117
	v_mul_f32_e32 v115, v121, v115
	v_exp_f32_e64 v117, -v122
	v_mul_f32_e32 v115, v115, v116
	v_exp_f32_e64 v116, -v123
	v_cvt_pk_bf16_f32 v114, v114, v115
	v_add_f32_e32 v115, 1.0, v117
	v_rcp_f32_e32 v115, v115
	v_add_f32_e32 v116, 1.0, v116
	v_rcp_f32_e32 v116, v116
	v_mul_lo_u32 v148, s26, v148
	v_add_u32_e32 v176, v148, v149
	v_mul_f32_e32 v117, v122, v150
	v_lshl_add_u64 v[154:155], v[176:177], 1, s[2:3]
	v_mul_f32_e32 v115, v117, v115
	v_mul_f32_e32 v117, v123, v151
	v_mul_f32_e32 v116, v117, v116
	v_cvt_pk_bf16_f32 v115, v115, v116
	global_store_dwordx4 v[154:155], v[112:115], off nt
	s_nop 0
	s_andn2_b64 vcc, exec, s[10:11]
	v_cndmask_b32_e64 v113, 0, 1, s[10:11]
	v_cmp_ne_u32_e64 s[8:9], 1, v113
	s_waitcnt vmcnt(7)
	v_fmamk_f32 v112, v180, 0x3a800000, v222
	v_rsq_f32_e32 v112, v112
	s_cbranch_vccnz .LBB0_551
	global_load_dword v113, v[146:147], off offset:64
	v_mul_f32_e32 v114, v112, v112
	s_waitcnt vmcnt(0)
	v_mul_f32_e32 v113, v114, v113
	v_fmamk_f32 v113, v113, 0x3a800000, v222
	v_rsq_f32_e32 v113, v113
	s_nop 0
	v_mul_f32_e32 v112, v112, v113
; __device__ __forceinline__ unsigned cvt_pk_bf16(float lo, float hi) { unsigned r; asm volatile("v_cvt_pk_bf16_f32 %0, %1, %2" : "=v"(r) : "v"(lo), "v"(hi)); return r; }
; #define SWG_(gv, uv) ((gv) * (uv) * __builtin_amdgcn_rcpf(1.0f + __builtin_amdgcn_exp2f(-(gv))))
;     __device__ __forceinline__ unsigned u(int i) const { return (unsigned)__builtin_amdgcn_readfirstlane((int)d[i]); }
; __device__ __forceinline__ float row_scale(const float* ssqA, const float* ssqB, int row) {
;     float r = __builtin_amdgcn_rsqf(ssqA[row] * (1.0f / 1024.0f) + 1e-6f);
;     if (ssqB) r *= __builtin_amdgcn_rsqf(r * r * ssqB[row] * (1.0f / 1024.0f) + 1e-6f);
;     return r;
; }
;     static __device__ __forceinline__ void run(const f32x4 (&acc)[2][2][4][2], const Unit& u, int wr, int wc, int fr, int fq, bf16_t* H, int ldh, const float* ssqA, const float* ssqB, const float* bvec) {
;         const int b = (u.pm * BM) >> 13; const int row0 = u.pm * BM + wr * 64 + fr; const int col0 = u.pn * 128 + wc * 32 + 8 * fq;
;         const float* bp = bvec + ((unsigned)b * (unsigned)(2 * ldh) + (unsigned)(u.pn * BM + wc * 32 + 8 * fq));
;         const f32x4 bg0 = *(const f32x4*)bp * 1.4426950408889634f, bg1 = *(const f32x4*)(bp + 4) * 1.4426950408889634f, bu0 = *(const f32x4*)(bp + HALF) * 0.6931471805599453f, bu1 = *(const f32x4*)(bp + HALF + 4) * 0.6931471805599453f;
;     ...
; #pragma unroll
;         for (int ai = 0; ai < 2; ++ai)
; #pragma unroll
;             for (int m = 0; m < 4; ++m) {
;                 const int row = row0 + ai * HALF + m * 16; const float r = row_scale(ssqA, ssqB, row); const float rg = r * 1.4426950408889634f, ru = r * 0.6931471805599453f;
;                 bf16_t* p = H + ((unsigned)row * (unsigned)ldh + (unsigned)col0);
;                 const f32x4 g0 = acc[ai][0][m][0] * rg + bg0, g1 = acc[ai][0][m][1] * rg + bg1, u0 = acc[ai][1][m][0] * ru + bu0, u1 = acc[ai][1][m][1] * ru + bu1;
;                 u32x4 w;
;                 w.x = cvt_pk_bf16(SWG_(g0[0], u0[0]), SWG_(g0[1], u0[1]));
;                 w.y = cvt_pk_bf16(SWG_(g0[2], u0[2]), SWG_(g0[3], u0[3]));
;                 w.z = cvt_pk_bf16(SWG_(g1[0], u1[0]), SWG_(g1[1], u1[1]));
;                 w.w = cvt_pk_bf16(SWG_(g1[2], u1[2]), SWG_(g1[3], u1[3]));
;                 __builtin_nontemporal_store(w, (u32x4*)p);
;                 asm volatile("" ::: "memory");
;             }
.LBB0_551:
	v_mul_f32_e32 v114, 0x3fb8aa3b, v112
	v_pk_fma_f32 v[108:109], v[108:109], v[114:115], v[140:141] op_sel_hi:[1,0,1]
	v_mul_f32_e32 v116, 0x3f317218, v112
	v_exp_f32_e64 v113, -v108
	v_pk_fma_f32 v[110:111], v[110:111], v[114:115], v[142:143] op_sel_hi:[1,0,1]
	v_pk_fma_f32 v[106:107], v[106:107], v[114:115], v[138:139] op_sel_hi:[1,0,1]
	v_pk_fma_f32 v[104:105], v[104:105], v[114:115], v[136:137] op_sel_hi:[1,0,1]
	v_pk_fma_f32 v[114:115], v[98:99], v[116:117], v[130:131] op_sel_hi:[1,0,1]
	v_pk_fma_f32 v[98:99], v[96:97], v[116:117], v[128:129] op_sel_hi:[1,0,1]
	v_exp_f32_e64 v96, -v109
	v_add_f32_e32 v97, 1.0, v113
	v_rcp_f32_e32 v97, v97
	v_pk_fma_f32 v[100:101], v[100:101], v[116:117], v[132:133] op_sel_hi:[1,0,1]
	v_add_f32_e32 v96, 1.0, v96
	v_rcp_f32_e32 v96, v96
	v_mul_f32_e32 v100, v108, v100
	v_mul_f32_e32 v97, v100, v97
	v_mul_f32_e32 v100, v109, v101
	v_exp_f32_e64 v101, -v110
	v_mul_f32_e32 v96, v100, v96
	v_cvt_pk_bf16_f32 v96, v97, v96
	v_exp_f32_e64 v97, -v111
	v_add_f32_e32 v100, 1.0, v101
	v_rcp_f32_e32 v100, v100
	v_pk_fma_f32 v[102:103], v[102:103], v[116:117], v[134:135] op_sel_hi:[1,0,1]
	v_add_f32_e32 v97, 1.0, v97
	v_rcp_f32_e32 v97, v97
	v_mul_f32_e32 v101, v110, v102
	v_mul_f32_e32 v100, v101, v100
	v_mul_f32_e32 v101, v111, v103
	v_exp_f32_e64 v102, -v104
	v_mul_f32_e32 v97, v101, v97
	v_cvt_pk_bf16_f32 v97, v100, v97
	v_exp_f32_e64 v100, -v105
	v_add_f32_e32 v101, 1.0, v102
	v_rcp_f32_e32 v101, v101
	v_mul_f32_e32 v98, v104, v98
	v_add_f32_e32 v100, 1.0, v100
	v_rcp_f32_e32 v100, v100
	v_mul_f32_e32 v98, v98, v101
	v_mul_f32_e32 v99, v105, v99
	v_exp_f32_e64 v101, -v106
	v_mul_f32_e32 v99, v99, v100
	v_exp_f32_e64 v100, -v107
	v_cvt_pk_bf16_f32 v98, v98, v99
	v_add_f32_e32 v99, 1.0, v101
	v_rcp_f32_e32 v99, v99
	v_add_f32_e32 v100, 1.0, v100
	s_lshl_b32 s10, s26, 4
	v_rcp_f32_e32 v100, v100
	v_add_u32_e32 v112, s10, v148
	v_add_u32_e32 v176, v112, v149
	v_mul_f32_e32 v101, v106, v114
	v_lshl_add_u64 v[118:119], v[176:177], 1, s[2:3]
	v_mul_f32_e32 v99, v101, v99
	v_mul_f32_e32 v101, v107, v115
	v_mul_f32_e32 v100, v101, v100
	v_cvt_pk_bf16_f32 v99, v99, v100
	global_store_dwordx4 v[118:119], v[96:99], off nt
	s_nop 0
	s_and_b64 vcc, exec, s[8:9]
	s_waitcnt vmcnt(7)
	v_fmamk_f32 v96, v181, 0x3a800000, v222
	v_rsq_f32_e32 v96, v96
	s_cbranch_vccnz .LBB0_553
	global_load_dword v97, v[146:147], off offset:128
	v_mul_f32_e32 v98, v96, v96
	s_waitcnt vmcnt(0)
	v_mul_f32_e32 v97, v98, v97
	v_fmamk_f32 v97, v97, 0x3a800000, v222
	v_rsq_f32_e32 v97, v97
	s_nop 0
	v_mul_f32_e32 v96, v96, v97
.LBB0_553:
	v_mul_f32_e32 v98, 0x3fb8aa3b, v96
	v_pk_fma_f32 v[92:93], v[92:93], v[98:99], v[140:141] op_sel_hi:[1,0,1]
	v_mul_f32_e32 v100, 0x3f317218, v96
	v_exp_f32_e64 v97, -v92
	v_pk_fma_f32 v[94:95], v[94:95], v[98:99], v[142:143] op_sel_hi:[1,0,1]
	v_pk_fma_f32 v[90:91], v[90:91], v[98:99], v[138:139] op_sel_hi:[1,0,1]
	v_pk_fma_f32 v[88:89], v[88:89], v[98:99], v[136:137] op_sel_hi:[1,0,1]
	v_pk_fma_f32 v[98:99], v[82:83], v[100:101], v[130:131] op_sel_hi:[1,0,1]
	v_pk_fma_f32 v[82:83], v[80:81], v[100:101], v[128:129] op_sel_hi:[1,0,1]
	v_exp_f32_e64 v80, -v93
	v_add_f32_e32 v81, 1.0, v97
	v_rcp_f32_e32 v81, v81
	v_pk_fma_f32 v[84:85], v[84:85], v[100:101], v[132:133] op_sel_hi:[1,0,1]
	v_add_f32_e32 v80, 1.0, v80
	v_rcp_f32_e32 v80, v80
	v_mul_f32_e32 v84, v92, v84
	v_mul_f32_e32 v81, v84, v81
	v_mul_f32_e32 v84, v93, v85
	v_exp_f32_e64 v85, -v94
	v_mul_f32_e32 v80, v84, v80
	v_cvt_pk_bf16_f32 v80, v81, v80
	v_exp_f32_e64 v81, -v95
	v_add_f32_e32 v84, 1.0, v85
	v_rcp_f32_e32 v84, v84
	v_pk_fma_f32 v[86:87], v[86:87], v[100:101], v[134:135] op_sel_hi:[1,0,1]
	v_add_f32_e32 v81, 1.0, v81
	v_rcp_f32_e32 v81, v81
	v_mul_f32_e32 v85, v94, v86
	v_mul_f32_e32 v84, v85, v84
	v_mul_f32_e32 v85, v95, v87
	v_exp_f32_e64 v86, -v88
	v_mul_f32_e32 v81, v85, v81
	v_cvt_pk_bf16_f32 v81, v84, v81
	v_exp_f32_e64 v84, -v89
	v_add_f32_e32 v85, 1.0, v86
	v_rcp_f32_e32 v85, v85
	v_mul_f32_e32 v82, v88, v82
	v_add_f32_e32 v84, 1.0, v84
	v_rcp_f32_e32 v84, v84
	v_mul_f32_e32 v82, v82, v85
	v_mul_f32_e32 v83, v89, v83
	v_exp_f32_e64 v85, -v90
	v_mul_f32_e32 v83, v83, v84
	v_exp_f32_e64 v84, -v91
	v_cvt_pk_bf16_f32 v82, v82, v83
	v_add_f32_e32 v83, 1.0, v85
	v_rcp_f32_e32 v83, v83
	v_add_f32_e32 v84, 1.0, v84
	v_rcp_f32_e32 v84, v84
	v_add_u32_e32 v96, s10, v112
	v_add_u32_e32 v176, v96, v149
	v_mul_f32_e32 v85, v90, v98
	v_lshl_add_u64 v[102:103], v[176:177], 1, s[2:3]
	v_mul_f32_e32 v83, v85, v83
	v_mul_f32_e32 v85, v91, v99
	v_mul_f32_e32 v84, v85, v84
	v_cvt_pk_bf16_f32 v83, v83, v84
	global_store_dwordx4 v[102:103], v[80:83], off nt
	s_nop 0
	s_and_b64 vcc, exec, s[8:9]
	s_waitcnt vmcnt(7)
	v_fmamk_f32 v80, v182, 0x3a800000, v222
	v_rsq_f32_e32 v80, v80
	s_cbranch_vccnz .LBB0_555
	global_load_dword v81, v[146:147], off offset:192
	v_mul_f32_e32 v82, v80, v80
	s_waitcnt vmcnt(0)
	v_mul_f32_e32 v81, v82, v81
	v_fmamk_f32 v81, v81, 0x3a800000, v222
	v_rsq_f32_e32 v81, v81
	s_nop 0
	v_mul_f32_e32 v80, v80, v81
; __device__ __forceinline__ unsigned cvt_pk_bf16(float lo, float hi) { unsigned r; asm volatile("v_cvt_pk_bf16_f32 %0, %1, %2" : "=v"(r) : "v"(lo), "v"(hi)); return r; }
; #define SWG_(gv, uv) ((gv) * (uv) * __builtin_amdgcn_rcpf(1.0f + __builtin_amdgcn_exp2f(-(gv))))
;     __device__ __forceinline__ unsigned u(int i) const { return (unsigned)__builtin_amdgcn_readfirstlane((int)d[i]); }
; __device__ __forceinline__ float row_scale(const float* ssqA, const float* ssqB, int row) {
;     float r = __builtin_amdgcn_rsqf(ssqA[row] * (1.0f / 1024.0f) + 1e-6f);
;     if (ssqB) r *= __builtin_amdgcn_rsqf(r * r * ssqB[row] * (1.0f / 1024.0f) + 1e-6f);
;     return r;
; }
;     static __device__ __forceinline__ void run(const f32x4 (&acc)[2][2][4][2], const Unit& u, int wr, int wc, int fr, int fq, bf16_t* H, int ldh, const float* ssqA, const float* ssqB, const float* bvec) {
;         const int b = (u.pm * BM) >> 13; const int row0 = u.pm * BM + wr * 64 + fr; const int col0 = u.pn * 128 + wc * 32 + 8 * fq;
;         const float* bp = bvec + ((unsigned)b * (unsigned)(2 * ldh) + (unsigned)(u.pn * BM + wc * 32 + 8 * fq));
;         const f32x4 bg0 = *(const f32x4*)bp * 1.4426950408889634f, bg1 = *(const f32x4*)(bp + 4) * 1.4426950408889634f, bu0 = *(const f32x4*)(bp + HALF) * 0.6931471805599453f, bu1 = *(const f32x4*)(bp + HALF + 4) * 0.6931471805599453f;
;     ...
; #pragma unroll
;         for (int ai = 0; ai < 2; ++ai)
; #pragma unroll
;             for (int m = 0; m < 4; ++m) {
;                 const int row = row0 + ai * HALF + m * 16; const float r = row_scale(ssqA, ssqB, row); const float rg = r * 1.4426950408889634f, ru = r * 0.6931471805599453f;
;                 bf16_t* p = H + ((unsigned)row * (unsigned)ldh + (unsigned)col0);
;                 const f32x4 g0 = acc[ai][0][m][0] * rg + bg0, g1 = acc[ai][0][m][1] * rg + bg1, u0 = acc[ai][1][m][0] * ru + bu0, u1 = acc[ai][1][m][1] * ru + bu1;
;                 u32x4 w;
;                 w.x = cvt_pk_bf16(SWG_(g0[0], u0[0]), SWG_(g0[1], u0[1]));
;                 w.y = cvt_pk_bf16(SWG_(g0[2], u0[2]), SWG_(g0[3], u0[3]));
;                 w.z = cvt_pk_bf16(SWG_(g1[0], u1[0]), SWG_(g1[1], u1[1]));
;                 w.w = cvt_pk_bf16(SWG_(g1[2], u1[2]), SWG_(g1[3], u1[3]));
;                 __builtin_nontemporal_store(w, (u32x4*)p);
;                 asm volatile("" ::: "memory");
;             }
.LBB0_555:
	v_mul_f32_e32 v82, 0x3fb8aa3b, v80
	v_pk_fma_f32 v[76:77], v[76:77], v[82:83], v[140:141] op_sel_hi:[1,0,1]
	v_mul_f32_e32 v84, 0x3f317218, v80
	v_exp_f32_e64 v81, -v76
	v_pk_fma_f32 v[78:79], v[78:79], v[82:83], v[142:143] op_sel_hi:[1,0,1]
	v_pk_fma_f32 v[74:75], v[74:75], v[82:83], v[138:139] op_sel_hi:[1,0,1]
	v_pk_fma_f32 v[72:73], v[72:73], v[82:83], v[136:137] op_sel_hi:[1,0,1]
	v_pk_fma_f32 v[82:83], v[66:67], v[84:85], v[130:131] op_sel_hi:[1,0,1]
	v_pk_fma_f32 v[66:67], v[64:65], v[84:85], v[128:129] op_sel_hi:[1,0,1]
	v_exp_f32_e64 v64, -v77
	v_add_f32_e32 v65, 1.0, v81
	v_rcp_f32_e32 v65, v65
	v_pk_fma_f32 v[68:69], v[68:69], v[84:85], v[132:133] op_sel_hi:[1,0,1]
	v_add_f32_e32 v64, 1.0, v64
	v_rcp_f32_e32 v64, v64
	v_mul_f32_e32 v68, v76, v68
	v_mul_f32_e32 v65, v68, v65
	v_mul_f32_e32 v68, v77, v69
	v_exp_f32_e64 v69, -v78
	v_mul_f32_e32 v64, v68, v64
	v_cvt_pk_bf16_f32 v64, v65, v64
	v_exp_f32_e64 v65, -v79
	v_add_f32_e32 v68, 1.0, v69
	v_rcp_f32_e32 v68, v68
	v_pk_fma_f32 v[70:71], v[70:71], v[84:85], v[134:135] op_sel_hi:[1,0,1]
	v_add_f32_e32 v65, 1.0, v65
	v_rcp_f32_e32 v65, v65
	v_mul_f32_e32 v69, v78, v70
	v_mul_f32_e32 v68, v69, v68
	v_mul_f32_e32 v69, v79, v71
	v_exp_f32_e64 v70, -v72
	v_mul_f32_e32 v65, v69, v65
	v_cvt_pk_bf16_f32 v65, v68, v65
	v_exp_f32_e64 v68, -v73
	v_add_f32_e32 v69, 1.0, v70
	v_rcp_f32_e32 v69, v69
	v_mul_f32_e32 v66, v72, v66
	v_add_f32_e32 v68, 1.0, v68
	v_rcp_f32_e32 v68, v68
	v_mul_f32_e32 v66, v66, v69
	v_mul_f32_e32 v67, v73, v67
	v_exp_f32_e64 v69, -v74
	v_mul_f32_e32 v67, v67, v68
	v_exp_f32_e64 v68, -v75
	v_cvt_pk_bf16_f32 v66, v66, v67
	v_add_f32_e32 v67, 1.0, v69
	v_rcp_f32_e32 v67, v67
	v_add_f32_e32 v68, 1.0, v68
	v_rcp_f32_e32 v68, v68
	v_add_u32_e32 v80, s10, v96
	v_add_u32_e32 v176, v80, v149
	v_mul_f32_e32 v69, v74, v82
	v_lshl_add_u64 v[86:87], v[176:177], 1, s[2:3]
	v_mul_f32_e32 v67, v69, v67
	v_mul_f32_e32 v69, v75, v83
	v_mul_f32_e32 v68, v69, v68
	v_cvt_pk_bf16_f32 v67, v67, v68
	global_store_dwordx4 v[86:87], v[64:67], off nt
	s_nop 0
	s_and_b64 vcc, exec, s[8:9]
	s_waitcnt vmcnt(7)
	v_fmamk_f32 v64, v183, 0x3a800000, v222
	v_rsq_f32_e32 v64, v64
	s_cbranch_vccnz .LBB0_557
	global_load_dword v65, v[146:147], off offset:512
	v_mul_f32_e32 v66, v64, v64
	s_waitcnt vmcnt(0)
	v_mul_f32_e32 v65, v66, v65
	v_fmamk_f32 v65, v65, 0x3a800000, v222
	v_rsq_f32_e32 v65, v65
	s_nop 0
	v_mul_f32_e32 v64, v64, v65
.LBB0_557:
	v_mul_f32_e32 v66, 0x3fb8aa3b, v64
	v_pk_fma_f32 v[60:61], v[60:61], v[66:67], v[140:141] op_sel_hi:[1,0,1]
	v_mul_f32_e32 v68, 0x3f317218, v64
	v_exp_f32_e64 v65, -v60
	v_pk_fma_f32 v[62:63], v[62:63], v[66:67], v[142:143] op_sel_hi:[1,0,1]
	v_pk_fma_f32 v[58:59], v[58:59], v[66:67], v[138:139] op_sel_hi:[1,0,1]
	v_pk_fma_f32 v[56:57], v[56:57], v[66:67], v[136:137] op_sel_hi:[1,0,1]
	v_pk_fma_f32 v[66:67], v[50:51], v[68:69], v[130:131] op_sel_hi:[1,0,1]
	v_pk_fma_f32 v[50:51], v[48:49], v[68:69], v[128:129] op_sel_hi:[1,0,1]
	v_exp_f32_e64 v48, -v61
	v_add_f32_e32 v49, 1.0, v65
	v_rcp_f32_e32 v49, v49
	v_pk_fma_f32 v[52:53], v[52:53], v[68:69], v[132:133] op_sel_hi:[1,0,1]
	v_add_f32_e32 v48, 1.0, v48
	v_rcp_f32_e32 v48, v48
	v_mul_f32_e32 v52, v60, v52
	v_mul_f32_e32 v49, v52, v49
	v_mul_f32_e32 v52, v61, v53
	v_exp_f32_e64 v53, -v62
	v_mul_f32_e32 v48, v52, v48
	v_cvt_pk_bf16_f32 v48, v49, v48
	v_exp_f32_e64 v49, -v63
	v_add_f32_e32 v52, 1.0, v53
	v_rcp_f32_e32 v52, v52
	v_pk_fma_f32 v[54:55], v[54:55], v[68:69], v[134:135] op_sel_hi:[1,0,1]
	v_add_f32_e32 v49, 1.0, v49
	v_rcp_f32_e32 v49, v49
	v_mul_f32_e32 v53, v62, v54
	v_mul_f32_e32 v52, v53, v52
	v_mul_f32_e32 v53, v63, v55
	v_exp_f32_e64 v54, -v56
	v_mul_f32_e32 v49, v53, v49
	v_cvt_pk_bf16_f32 v49, v52, v49
	v_exp_f32_e64 v52, -v57
	v_add_f32_e32 v53, 1.0, v54
	v_rcp_f32_e32 v53, v53
	v_mul_f32_e32 v50, v56, v50
	v_add_f32_e32 v52, 1.0, v52
	v_rcp_f32_e32 v52, v52
	v_mul_f32_e32 v50, v50, v53
	v_mul_f32_e32 v51, v57, v51
	v_exp_f32_e64 v53, -v58
	v_mul_f32_e32 v51, v51, v52
	v_exp_f32_e64 v52, -v59
	v_cvt_pk_bf16_f32 v50, v50, v51
	v_add_f32_e32 v51, 1.0, v53
	v_rcp_f32_e32 v51, v51
	v_add_f32_e32 v52, 1.0, v52
	s_mulk_i32 s26, 0x50
	v_rcp_f32_e32 v52, v52
	v_add_u32_e32 v64, s26, v80
	v_add_u32_e32 v176, v64, v149
	v_mul_f32_e32 v53, v58, v66
	v_lshl_add_u64 v[70:71], v[176:177], 1, s[2:3]
	v_mul_f32_e32 v51, v53, v51
	v_mul_f32_e32 v53, v59, v67
	v_mul_f32_e32 v52, v53, v52
	v_cvt_pk_bf16_f32 v51, v51, v52
	global_store_dwordx4 v[70:71], v[48:51], off nt
	s_nop 0
	s_and_b64 vcc, exec, s[8:9]
	s_waitcnt vmcnt(7)
	v_fmamk_f32 v48, v184, 0x3a800000, v222
	v_rsq_f32_e32 v48, v48
	s_cbranch_vccnz .LBB0_559
	global_load_dword v49, v[146:147], off offset:576
	v_mul_f32_e32 v50, v48, v48
	s_waitcnt vmcnt(0)
	v_mul_f32_e32 v49, v50, v49
	v_fmamk_f32 v49, v49, 0x3a800000, v222
	v_rsq_f32_e32 v49, v49
	s_nop 0
	v_mul_f32_e32 v48, v48, v49
; __device__ __forceinline__ unsigned cvt_pk_bf16(float lo, float hi) { unsigned r; asm volatile("v_cvt_pk_bf16_f32 %0, %1, %2" : "=v"(r) : "v"(lo), "v"(hi)); return r; }
; #define SWG_(gv, uv) ((gv) * (uv) * __builtin_amdgcn_rcpf(1.0f + __builtin_amdgcn_exp2f(-(gv))))
;     __device__ __forceinline__ unsigned u(int i) const { return (unsigned)__builtin_amdgcn_readfirstlane((int)d[i]); }
; __device__ __forceinline__ float row_scale(const float* ssqA, const float* ssqB, int row) {
;     float r = __builtin_amdgcn_rsqf(ssqA[row] * (1.0f / 1024.0f) + 1e-6f);
;     if (ssqB) r *= __builtin_amdgcn_rsqf(r * r * ssqB[row] * (1.0f / 1024.0f) + 1e-6f);
;     return r;
; }
;     static __device__ __forceinline__ void run(const f32x4 (&acc)[2][2][4][2], const Unit& u, int wr, int wc, int fr, int fq, bf16_t* H, int ldh, const float* ssqA, const float* ssqB, const float* bvec) {
;         const int b = (u.pm * BM) >> 13; const int row0 = u.pm * BM + wr * 64 + fr; const int col0 = u.pn * 128 + wc * 32 + 8 * fq;
;         const float* bp = bvec + ((unsigned)b * (unsigned)(2 * ldh) + (unsigned)(u.pn * BM + wc * 32 + 8 * fq));
;         const f32x4 bg0 = *(const f32x4*)bp * 1.4426950408889634f, bg1 = *(const f32x4*)(bp + 4) * 1.4426950408889634f, bu0 = *(const f32x4*)(bp + HALF) * 0.6931471805599453f, bu1 = *(const f32x4*)(bp + HALF + 4) * 0.6931471805599453f;
;     ...
; #pragma unroll
;         for (int ai = 0; ai < 2; ++ai)
; #pragma unroll
;             for (int m = 0; m < 4; ++m) {
;                 const int row = row0 + ai * HALF + m * 16; const float r = row_scale(ssqA, ssqB, row); const float rg = r * 1.4426950408889634f, ru = r * 0.6931471805599453f;
;                 bf16_t* p = H + ((unsigned)row * (unsigned)ldh + (unsigned)col0);
;                 const f32x4 g0 = acc[ai][0][m][0] * rg + bg0, g1 = acc[ai][0][m][1] * rg + bg1, u0 = acc[ai][1][m][0] * ru + bu0, u1 = acc[ai][1][m][1] * ru + bu1;
;                 u32x4 w;
;                 w.x = cvt_pk_bf16(SWG_(g0[0], u0[0]), SWG_(g0[1], u0[1]));
;                 w.y = cvt_pk_bf16(SWG_(g0[2], u0[2]), SWG_(g0[3], u0[3]));
;                 w.z = cvt_pk_bf16(SWG_(g1[0], u1[0]), SWG_(g1[1], u1[1]));
;                 w.w = cvt_pk_bf16(SWG_(g1[2], u1[2]), SWG_(g1[3], u1[3]));
;                 __builtin_nontemporal_store(w, (u32x4*)p);
;                 asm volatile("" ::: "memory");
;             }
.LBB0_559:
	v_mul_f32_e32 v50, 0x3fb8aa3b, v48
	v_pk_fma_f32 v[44:45], v[44:45], v[50:51], v[140:141] op_sel_hi:[1,0,1]
	v_mul_f32_e32 v52, 0x3f317218, v48
	v_exp_f32_e64 v49, -v44
	v_pk_fma_f32 v[46:47], v[46:47], v[50:51], v[142:143] op_sel_hi:[1,0,1]
	v_pk_fma_f32 v[42:43], v[42:43], v[50:51], v[138:139] op_sel_hi:[1,0,1]
	v_pk_fma_f32 v[40:41], v[40:41], v[50:51], v[136:137] op_sel_hi:[1,0,1]
	v_pk_fma_f32 v[50:51], v[34:35], v[52:53], v[130:131] op_sel_hi:[1,0,1]
	v_pk_fma_f32 v[34:35], v[32:33], v[52:53], v[128:129] op_sel_hi:[1,0,1]
	v_exp_f32_e64 v32, -v45
	v_add_f32_e32 v33, 1.0, v49
	v_rcp_f32_e32 v33, v33
	v_pk_fma_f32 v[36:37], v[36:37], v[52:53], v[132:133] op_sel_hi:[1,0,1]
	v_add_f32_e32 v32, 1.0, v32
	v_rcp_f32_e32 v32, v32
	v_mul_f32_e32 v36, v44, v36
	v_mul_f32_e32 v33, v36, v33
	v_mul_f32_e32 v36, v45, v37
	v_exp_f32_e64 v37, -v46
	v_mul_f32_e32 v32, v36, v32
	v_cvt_pk_bf16_f32 v32, v33, v32
	v_exp_f32_e64 v33, -v47
	v_add_f32_e32 v36, 1.0, v37
	v_rcp_f32_e32 v36, v36
	v_pk_fma_f32 v[38:39], v[38:39], v[52:53], v[134:135] op_sel_hi:[1,0,1]
	v_add_f32_e32 v33, 1.0, v33
	v_rcp_f32_e32 v33, v33
	v_mul_f32_e32 v37, v46, v38
	v_mul_f32_e32 v36, v37, v36
	v_mul_f32_e32 v37, v47, v39
	v_exp_f32_e64 v38, -v40
	v_mul_f32_e32 v33, v37, v33
	v_cvt_pk_bf16_f32 v33, v36, v33
	v_exp_f32_e64 v36, -v41
	v_add_f32_e32 v37, 1.0, v38
	v_rcp_f32_e32 v37, v37
	v_mul_f32_e32 v34, v40, v34
	v_add_f32_e32 v36, 1.0, v36
	v_rcp_f32_e32 v36, v36
	v_mul_f32_e32 v34, v34, v37
	v_mul_f32_e32 v35, v41, v35
	v_exp_f32_e64 v37, -v42
	v_mul_f32_e32 v35, v35, v36
	v_exp_f32_e64 v36, -v43
	v_cvt_pk_bf16_f32 v34, v34, v35
	v_add_f32_e32 v35, 1.0, v37
	v_rcp_f32_e32 v35, v35
	v_add_f32_e32 v36, 1.0, v36
	v_rcp_f32_e32 v36, v36
	v_add_u32_e32 v48, s10, v64
	v_add_u32_e32 v176, v48, v149
	v_mul_f32_e32 v37, v42, v50
	v_lshl_add_u64 v[54:55], v[176:177], 1, s[2:3]
	v_mul_f32_e32 v35, v37, v35
	v_mul_f32_e32 v37, v43, v51
	v_mul_f32_e32 v36, v37, v36
	v_cvt_pk_bf16_f32 v35, v35, v36
	global_store_dwordx4 v[54:55], v[32:35], off nt
	s_nop 0
	s_and_b64 vcc, exec, s[8:9]
	s_waitcnt vmcnt(7)
	v_fmamk_f32 v32, v185, 0x3a800000, v222
	v_rsq_f32_e32 v32, v32
	s_cbranch_vccnz .LBB0_561
	global_load_dword v33, v[146:147], off offset:640
	v_mul_f32_e32 v34, v32, v32
	s_waitcnt vmcnt(0)
	v_mul_f32_e32 v33, v34, v33
	v_fmamk_f32 v33, v33, 0x3a800000, v222
	v_rsq_f32_e32 v33, v33
	s_nop 0
	v_mul_f32_e32 v32, v32, v33
.LBB0_561:
	v_mul_f32_e32 v34, 0x3fb8aa3b, v32
	v_pk_fma_f32 v[28:29], v[28:29], v[34:35], v[140:141] op_sel_hi:[1,0,1]
	v_mul_f32_e32 v36, 0x3f317218, v32
	v_exp_f32_e64 v33, -v28
	v_pk_fma_f32 v[30:31], v[30:31], v[34:35], v[142:143] op_sel_hi:[1,0,1]
	v_pk_fma_f32 v[26:27], v[26:27], v[34:35], v[138:139] op_sel_hi:[1,0,1]
	v_pk_fma_f32 v[24:25], v[24:25], v[34:35], v[136:137] op_sel_hi:[1,0,1]
	v_pk_fma_f32 v[34:35], v[18:19], v[36:37], v[130:131] op_sel_hi:[1,0,1]
	v_pk_fma_f32 v[18:19], v[16:17], v[36:37], v[128:129] op_sel_hi:[1,0,1]
	v_exp_f32_e64 v16, -v29
	v_add_f32_e32 v17, 1.0, v33
	v_rcp_f32_e32 v17, v17
	v_pk_fma_f32 v[20:21], v[20:21], v[36:37], v[132:133] op_sel_hi:[1,0,1]
	v_add_f32_e32 v16, 1.0, v16
	v_rcp_f32_e32 v16, v16
	v_mul_f32_e32 v20, v28, v20
	v_mul_f32_e32 v17, v20, v17
	v_mul_f32_e32 v20, v29, v21
	v_exp_f32_e64 v21, -v30
	v_mul_f32_e32 v16, v20, v16
	v_cvt_pk_bf16_f32 v16, v17, v16
	v_exp_f32_e64 v17, -v31
	v_add_f32_e32 v20, 1.0, v21
	v_rcp_f32_e32 v20, v20
	v_pk_fma_f32 v[22:23], v[22:23], v[36:37], v[134:135] op_sel_hi:[1,0,1]
	v_add_f32_e32 v17, 1.0, v17
	v_rcp_f32_e32 v17, v17
	v_mul_f32_e32 v21, v30, v22
	v_mul_f32_e32 v20, v21, v20
	v_mul_f32_e32 v21, v31, v23
	v_exp_f32_e64 v22, -v24
	v_mul_f32_e32 v17, v21, v17
	v_cvt_pk_bf16_f32 v17, v20, v17
	v_exp_f32_e64 v20, -v25
	v_add_f32_e32 v21, 1.0, v22
	v_rcp_f32_e32 v21, v21
	v_mul_f32_e32 v18, v24, v18
	v_add_f32_e32 v20, 1.0, v20
	v_rcp_f32_e32 v20, v20
	v_mul_f32_e32 v18, v18, v21
	v_mul_f32_e32 v19, v25, v19
	v_exp_f32_e64 v21, -v26
	v_mul_f32_e32 v19, v19, v20
	v_exp_f32_e64 v20, -v27
	v_cvt_pk_bf16_f32 v18, v18, v19
	v_add_f32_e32 v19, 1.0, v21
	v_rcp_f32_e32 v19, v19
	v_add_f32_e32 v20, 1.0, v20
	v_rcp_f32_e32 v20, v20
	v_add_u32_e32 v32, s10, v48
	v_add_u32_e32 v176, v32, v149
	v_mul_f32_e32 v21, v26, v34
	v_lshl_add_u64 v[38:39], v[176:177], 1, s[2:3]
	v_mul_f32_e32 v19, v21, v19
	v_mul_f32_e32 v21, v27, v35
	v_mul_f32_e32 v20, v21, v20
	v_cvt_pk_bf16_f32 v19, v19, v20
	global_store_dwordx4 v[38:39], v[16:19], off nt
	s_nop 0
	s_and_b64 vcc, exec, s[8:9]
	s_waitcnt vmcnt(7)
	v_fmamk_f32 v16, v186, 0x3a800000, v222
	v_rsq_f32_e32 v16, v16
	s_cbranch_vccnz .LBB0_563
	global_load_dword v17, v[146:147], off offset:704
	v_mul_f32_e32 v18, v16, v16
	s_waitcnt vmcnt(0)
	v_mul_f32_e32 v17, v18, v17
	v_fmamk_f32 v17, v17, 0x3a800000, v222
	v_rsq_f32_e32 v17, v17
	s_nop 0
	v_mul_f32_e32 v16, v16, v17

; __device__ __forceinline__ float wave_sum(float v) { v = xadd<1>(v); v = xadd<2>(v); v = xadd<4>(v); v = xadd<8>(v); v = xadd<16>(v); return xadd<32>(v); }
; __device__ __forceinline__ void norm_phase(const float* xsrc, float* xdst, const float* gout, bf16* a, const float* g, const float* sh, const float* sc, int mode, int gw, int NGW, int lane) {
;     for (int row = gw; row < M; row += NGW) {
;         const int b = row >> 13;
;         const f32x4* xr = (const f32x4*)(xsrc + (size_t)row * D) + lane;
;         f32x4 v[4];
; #pragma unroll
;         for (int j = 0; j < 4; ++j) v[j] = xr[64 * j];
;         if (mode >= 1) {
;             float ss = 0.f;
; #pragma unroll
;             for (int j = 0; j < 4; ++j) ss += (v[j].x * v[j].x + v[j].y * v[j].y) + (v[j].z * v[j].z + v[j].w * v[j].w);
;             const float rs = 1.0f / sqrtf(wave_sum(ss) * (1.0f / D) + 1e-6f);
;             f32x4* xo = (f32x4*)(xdst + (size_t)row * D) + lane;
; #pragma unroll
;             for (int j = 0; j < 4; ++j) { const f32x4 gg = *((const f32x4*)gout + lane + 64 * j); v[j] = v[j] * rs * gg; xo[64 * j] = v[j]; }
;         }
.LBB0_611:
	global_load_dwordx4 v[32:35], v[0:1], off
	global_load_dwordx4 v[36:39], v[0:1], off offset:1024
	global_load_dwordx4 v[40:43], v[0:1], off offset:2048
	global_load_dwordx4 v[44:47], v[0:1], off offset:3072
	global_load_dwordx4 v[48:51], v[2:3], off offset:-2048
	global_load_dwordx4 v[52:55], v[2:3], off offset:-1024
	global_load_dwordx4 v[56:59], v[2:3], off
	global_load_dwordx4 v[60:63], v[2:3], off offset:1024
	s_waitcnt vmcnt(0)
	s_branch .Lnorm_enter
.Lnorm_loop:
	s_waitcnt vmcnt(4)
.Lnorm_enter:
	v_mov_b64_e32 v[4:5], v[48:49]
	v_mov_b64_e32 v[6:7], v[50:51]
	v_mov_b64_e32 v[8:9], v[52:53]
	v_mov_b64_e32 v[10:11], v[54:55]
	v_mov_b64_e32 v[12:13], v[56:57]
	v_mov_b64_e32 v[14:15], v[58:59]
	v_mov_b64_e32 v[16:17], v[60:61]
	v_mov_b64_e32 v[18:19], v[62:63]
	s_add_i32 s3, s3, s2
	s_cmpk_gt_i32 s3, 0x7fff
	s_cbranch_scc1 .Lnorm_nonext
	v_lshl_add_u64 v[64:65], v[2:3], 0, s[6:7]
	global_load_dwordx4 v[48:51], v[64:65], off offset:-2048
	global_load_dwordx4 v[52:55], v[64:65], off offset:-1024
	global_load_dwordx4 v[56:59], v[64:65], off
	global_load_dwordx4 v[60:63], v[64:65], off offset:1024
.Lnorm_nonext:
	v_mul_f32_e32 v24, v5, v5
	v_mul_f32_e32 v25, v7, v7
	v_mul_f32_e32 v26, v9, v9
	v_mul_f32_e32 v27, v11, v11
	v_mul_f32_e32 v28, v13, v13
	v_mul_f32_e32 v29, v15, v15
	v_fmac_f32_e32 v24, v4, v4
	v_fmac_f32_e32 v25, v6, v6
	v_fmac_f32_e32 v26, v8, v8
	v_fmac_f32_e32 v27, v10, v10
	v_mul_f32_e32 v30, v17, v17
	v_mul_f32_e32 v31, v19, v19
	v_fmac_f32_e32 v28, v12, v12
	v_fmac_f32_e32 v29, v14, v14
	v_add_f32_e32 v24, v24, v25
	v_add_f32_e32 v25, v26, v27
	v_fmac_f32_e32 v30, v16, v16
	v_fmac_f32_e32 v31, v18, v18
	v_add_f32_e32 v26, v28, v29
	v_add_f32_e32 v24, v24, v25
	v_add_f32_e32 v27, v30, v31
	v_add_f32_e32 v24, v24, v26
	v_add_f32_e32 v24, v24, v27
	ds_swizzle_b32 v25, v24 offset:swizzle(SWAP,1)
	s_waitcnt lgkmcnt(0)
	v_add_f32_e32 v24, v24, v25
	ds_swizzle_b32 v25, v24 offset:swizzle(SWAP,2)
	s_waitcnt lgkmcnt(0)
	v_add_f32_e32 v24, v24, v25
	ds_swizzle_b32 v25, v24 offset:swizzle(SWAP,4)
	s_waitcnt lgkmcnt(0)
	v_add_f32_e32 v24, v24, v25
	ds_swizzle_b32 v25, v24 offset:swizzle(SWAP,8)
	s_waitcnt lgkmcnt(0)
	v_add_f32_e32 v24, v24, v25
	ds_swizzle_b32 v25, v24 offset:swizzle(SWAP,16)
	s_waitcnt lgkmcnt(0)
	v_add_f32_e32 v24, v24, v25
	v_mov_b32_e32 v25, v24
	s_nop 1
	v_permlane32_swap_b32_e32 v24, v25
	v_add_f32_e32 v24, v24, v25
	v_fmamk_f32 v24, v24, 0x3a800000, v222
	v_mul_f32_e32 v25, 0x4f800000, v24
	v_cmp_gt_f32_e32 vcc, s97, v24
	s_nop 1
	v_cndmask_b32_e32 v24, v24, v25, vcc
	v_sqrt_f32_e32 v25, v24
	s_nop 0
	v_add_u32_e32 v26, -1, v25
	v_add_u32_e32 v27, 1, v25
	v_fma_f32 v28, -v26, v25, v24
	v_fma_f32 v29, -v27, v25, v24
	v_cmp_ge_f32_e64 s[0:1], 0, v28
	s_nop 1
	v_cndmask_b32_e64 v25, v25, v26, s[0:1]
	v_cmp_lt_f32_e64 s[0:1], 0, v29
	s_nop 1
	v_cndmask_b32_e64 v25, v25, v27, s[0:1]
	v_mul_f32_e32 v26, 0x37800000, v25
	v_cndmask_b32_e32 v25, v25, v26, vcc
	v_cmp_class_f32_e32 vcc, v24, v221
	s_nop 1
	v_cndmask_b32_e32 v24, v25, v24, vcc
	v_div_scale_f32 v25, s[0:1], v24, v24, 1.0
	v_rcp_f32_e32 v26, v25
	v_div_scale_f32 v27, vcc, 1.0, v24, 1.0
	v_fma_f32 v28, -v25, v26, 1.0
	v_fmac_f32_e32 v26, v28, v26
	v_mul_f32_e32 v28, v27, v26
	v_fma_f32 v29, -v25, v28, v27
	v_fmac_f32_e32 v28, v29, v26
	v_fma_f32 v25, -v25, v28, v27
	v_div_fmas_f32 v25, v25, v26, v28
	v_div_fixup_f32 v24, v25, v24, 1.0
	v_pk_mul_f32 v[4:5], v[4:5], v[24:25] op_sel_hi:[1,0]
	v_pk_mul_f32 v[6:7], v[6:7], v[24:25] op_sel_hi:[1,0]
	v_pk_mul_f32 v[4:5], v[32:33], v[4:5]
	v_pk_mul_f32 v[6:7], v[34:35], v[6:7]
	global_store_dwordx4 v[2:3], v[4:7], off offset:-2048
	v_pk_mul_f32 v[8:9], v[8:9], v[24:25] op_sel_hi:[1,0]
	v_pk_mul_f32 v[10:11], v[10:11], v[24:25] op_sel_hi:[1,0]
	v_pk_mul_f32 v[8:9], v[36:37], v[8:9]
	v_pk_mul_f32 v[10:11], v[38:39], v[10:11]
	global_store_dwordx4 v[2:3], v[8:11], off offset:-1024
	v_pk_mul_f32 v[12:13], v[12:13], v[24:25] op_sel_hi:[1,0]
	v_pk_mul_f32 v[14:15], v[14:15], v[24:25] op_sel_hi:[1,0]
	v_pk_mul_f32 v[12:13], v[40:41], v[12:13]
	v_pk_mul_f32 v[14:15], v[42:43], v[14:15]
	global_store_dwordx4 v[2:3], v[12:15], off
	v_pk_mul_f32 v[16:17], v[16:17], v[24:25] op_sel_hi:[1,0]
	v_pk_mul_f32 v[18:19], v[18:19], v[24:25] op_sel_hi:[1,0]
	v_pk_mul_f32 v[16:17], v[44:45], v[16:17]
	v_pk_mul_f32 v[18:19], v[46:47], v[18:19]
	global_store_dwordx4 v[2:3], v[16:19], off offset:1024
	v_lshl_add_u64 v[2:3], v[2:3], 0, s[6:7]
	s_cbranch_scc0 .Lnorm_loop
